# sample-tile epilogues of GEMM1, inb and both PLE phases: serialized per-row loads and second-GEMM fragment loads issued at tile start
# baseline (speedup 1.0000x reference)
.LBB0_75:
	s_and_b32 s3, s41, 0xffffffe0
	v_or_b32_e32 v0, s3, v40
	v_ashrrev_i32_e32 v1, 31, v0
	s_and_b32 s3, s40, 0x60
	v_lshlrev_b64 v[34:35], 11, v[0:1]
	v_add_lshl_u32 v144, v44, s3, 11
	s_mov_b64 s[4:5], 0x2600080
	v_mov_b32_e32 v0, 0
	s_lshl_b32 s2, s42, 5
	s_and_b32 s2, s2, 0x60
	v_add_u32_e32 v204, s2, v43
	v_add_u32_e32 v204, 0x4000, v204
	v_ashrrev_i32_e32 v205, 31, v204
	v_lshl_add_u64 v[204:205], v[204:205], 2, s[10:11]
	global_load_dwordx4 v[200:203], v[204:205], off
	s_movk_i32 s2, 0xffe0
	v_lshl_add_u64 v[36:37], v[144:145], 0, s[4:5]
	v_mov_b64_e32 v[38:39], v[32:33]
	v_mov_b32_e32 v1, v0
	v_mov_b32_e32 v2, v0
	v_mov_b32_e32 v3, v0
	v_mov_b32_e32 v4, v0
	v_mov_b32_e32 v5, v0
	v_mov_b32_e32 v6, v0
	v_mov_b32_e32 v7, v0
	v_mov_b32_e32 v8, v0
	v_mov_b32_e32 v9, v0
	v_mov_b32_e32 v10, v0
	v_mov_b32_e32 v11, v0
	v_mov_b32_e32 v12, v0
	v_mov_b32_e32 v13, v0
	v_mov_b32_e32 v14, v0
	v_mov_b32_e32 v15, v0
	v_mov_b32_e32 v16, v0
	v_mov_b32_e32 v17, v0
	v_mov_b32_e32 v18, v0
	v_mov_b32_e32 v19, v0
	v_mov_b32_e32 v20, v0
	v_mov_b32_e32 v21, v0
	v_mov_b32_e32 v22, v0
	v_mov_b32_e32 v23, v0
	v_mov_b32_e32 v24, v0
	v_mov_b32_e32 v25, v0
	v_mov_b32_e32 v26, v0
	v_mov_b32_e32 v27, v0
	v_mov_b32_e32 v28, v0
	v_mov_b32_e32 v29, v0
	v_mov_b32_e32 v30, v0
	v_mov_b32_e32 v31, v0

.LBB0_79:
	s_lshl_b32 s3, s42, 5
	s_and_b32 s3, s3, 0x60
	v_add_u32_e32 v8, s3, v43
	v_add_u32_e32 v8, 0x4000, v8
	v_ashrrev_i32_e32 v9, 31, v8
	v_lshl_add_u64 v[18:19], v[8:9], 2, s[10:11]
	s_waitcnt lgkmcnt(6)
	v_add_f32_e32 v10, v10, v14
	s_waitcnt lgkmcnt(3)
	v_add_f32_e32 v10, v10, v16
	s_waitcnt lgkmcnt(2)
	v_add_f32_e32 v10, v10, v12
	s_cmp_eq_u32 s2, 2
	s_cselect_b64 s[2:3], -1, 0
	s_mov_b64 s[4:5], -1
	s_waitcnt vmcnt(0)
	v_fmamk_f32 v18, v200, 0x3a800000, v176
	v_mul_f32_e32 v19, 0x4b800000, v18
	v_cmp_gt_f32_e32 vcc, s63, v18
	s_nop 1
	v_cndmask_b32_e32 v18, v18, v19, vcc
	v_rsq_f32_e32 v18, v18
	s_nop 0
	v_mul_f32_e32 v12, 0x45800000, v18
	v_cndmask_b32_e32 v12, v18, v12, vcc
	v_mul_f32_e32 v14, v10, v12
	v_mul_f32_e32 v10, 0xbfb8aa3b, v14
	v_exp_f32_e32 v10, v10
	s_and_b64 vcc, exec, s[36:37]
	v_add_f32_e32 v10, 1.0, v10
	v_rcp_f32_e32 v12, v10
	s_cbranch_vccz .LBB0_81
	v_mul_f32_e32 v10, v14, v12
	v_cndmask_b32_e64 v10, v10, v14, s[2:3]
	s_mov_b64 s[4:5], 0

.LBB0_83:
	v_or_b32_e32 v18, 1, v8
	v_ashrrev_i32_e32 v19, 31, v18
	v_lshl_add_u64 v[22:23], v[18:19], 2, s[10:11]
	v_add_f32_e32 v11, v11, v15
	v_cvt_pk_bf16_f32 v15, v10, s0
	v_add_f32_e32 v21, v11, v17
	s_ashr_i32 s38, s42, 4
	v_and_b32_e32 v16, 0x7f, v144
	v_lshlrev_b32_e32 v144, 1, v16
	v_mad_i64_i32 v[16:17], s[4:5], s38, v177, v[8:9]
	v_add_f32_e32 v9, v21, v13
	v_lshlrev_b64 v[16:17], 8, v[16:17]
	s_nop 0
	v_fmamk_f32 v10, v201, 0x3a800000, v176
	v_mul_f32_e32 v11, 0x4b800000, v10
	v_cmp_gt_f32_e32 vcc, s63, v10
	s_nop 1
	v_cndmask_b32_e32 v10, v10, v11, vcc
	v_rsq_f32_e32 v12, v10
	v_lshl_add_u64 v[10:11], s[6:7], 0, v[144:145]
	v_lshl_add_u64 v[16:17], v[10:11], 0, v[16:17]
	global_store_short v[16:17], v15, off
	v_mul_f32_e32 v13, 0x45800000, v12
	v_cndmask_b32_e32 v12, v12, v13, vcc
	v_mul_f32_e32 v13, v9, v12
	v_mul_f32_e32 v9, 0xbfb8aa3b, v13
	v_exp_f32_e32 v9, v9
	s_andn2_b64 vcc, exec, s[36:37]
	v_add_f32_e32 v9, 1.0, v9
	v_rcp_f32_e32 v12, v9
	v_cndmask_b32_e64 v9, 0, 1, s[36:37]
	v_cmp_ne_u32_e64 s[4:5], 1, v9
	s_mov_b64 s[36:37], -1
	s_cbranch_vccnz .LBB0_85
	v_mul_f32_e32 v9, v13, v12
	v_cndmask_b32_e64 v9, v9, v13, s[2:3]
	s_mov_b64 s[36:37], 0

.LBB0_87:
	v_or_b32_e32 v12, 2, v8
	v_ashrrev_i32_e32 v13, 31, v12
	v_lshl_add_u64 v[16:17], v[12:13], 2, s[10:11]
	v_add_f32_e32 v4, v6, v4
	s_waitcnt lgkmcnt(0)
	v_add_f32_e32 v2, v4, v2
	v_add_f32_e32 v0, v2, v0
	s_mul_hi_i32 s37, s38, 0x4080
	s_mul_i32 s36, s38, 0x4080
	v_lshl_add_u64 v[16:17], s[36:37], 0, v[18:19]
	v_lshlrev_b64 v[16:17], 8, v[16:17]
	v_cvt_pk_bf16_f32 v9, v9, s0
	v_lshl_add_u64 v[16:17], v[10:11], 0, v[16:17]
	s_mov_b64 s[38:39], -1
	global_store_short v[16:17], v9, off
	s_nop 0
	v_fmamk_f32 v6, v202, 0x3a800000, v176
	v_mul_f32_e32 v15, 0x4b800000, v6
	v_cmp_gt_f32_e32 vcc, s63, v6
	s_nop 1
	v_cndmask_b32_e32 v6, v6, v15, vcc
	v_rsq_f32_e32 v6, v6
	s_nop 0
	v_mul_f32_e32 v2, 0x45800000, v6
	v_cndmask_b32_e32 v2, v6, v2, vcc
	v_mul_f32_e32 v4, v0, v2
	v_mul_f32_e32 v0, 0xbfb8aa3b, v4
	v_exp_f32_e32 v0, v0
	s_and_b64 vcc, exec, s[4:5]
	v_add_f32_e32 v0, 1.0, v0
	v_rcp_f32_e32 v2, v0
	s_cbranch_vccnz .LBB0_89
	v_mul_f32_e32 v0, v4, v2
	v_cndmask_b32_e64 v0, v0, v4, s[2:3]
	s_mov_b64 s[38:39], 0

.LBB0_91:
	v_or_b32_e32 v8, 3, v8
	v_ashrrev_i32_e32 v9, 31, v8
	v_lshl_add_u64 v[16:17], v[8:9], 2, s[10:11]
	v_add_f32_e32 v4, v7, v5
	v_add_f32_e32 v3, v4, v3
	v_add_f32_e32 v1, v3, v1
	v_cvt_pk_bf16_f32 v3, v0, s0
	s_nop 0
	v_fmamk_f32 v2, v203, 0x3a800000, v176
	v_mul_f32_e32 v5, 0x4b800000, v2
	v_cmp_gt_f32_e32 vcc, s63, v2
	s_nop 1
	v_cndmask_b32_e32 v2, v2, v5, vcc
	v_rsq_f32_e32 v2, v2
	s_nop 0
	v_mul_f32_e32 v0, 0x45800000, v2
	v_cndmask_b32_e32 v0, v2, v0, vcc
	v_mul_f32_e32 v2, v1, v0
	v_mul_f32_e32 v0, 0xbfb8aa3b, v2
	v_exp_f32_e32 v6, v0
	v_lshl_add_u64 v[0:1], s[36:37], 0, v[12:13]
	v_lshlrev_b64 v[0:1], 8, v[0:1]
	v_lshl_add_u64 v[4:5], v[10:11], 0, v[0:1]
	v_add_f32_e32 v0, 1.0, v6
	v_rcp_f32_e32 v0, v0
	s_and_b64 vcc, exec, s[4:5]
	s_mov_b64 s[4:5], -1
	global_store_short v[4:5], v3, off
	s_cbranch_vccnz .LBB0_93
	v_mul_f32_e32 v1, v2, v0
	v_cndmask_b32_e64 v1, v1, v2, s[2:3]
	s_mov_b64 s[4:5], 0

.LBB0_724:
	s_and_b32 s6, s12, 0xffffffe0
	v_or_b32_e32 v0, s6, v62
	s_waitcnt lgkmcnt(0)
	v_ashrrev_i32_e32 v1, 31, v0
	v_lshlrev_b64 v[0:1], 11, v[0:1]
	s_and_b32 s6, s14, 0x60
	v_lshl_add_u64 v[42:43], v[38:39], 0, v[0:1]
	v_add_lshl_u32 v32, v71, s6, 11
	v_mov_b32_e32 v0, 0
	v_lshl_add_u64 v[44:45], v[40:41], 0, v[32:33]
	s_lshl_b32 s18, s16, 5
	s_and_b32 s18, s18, 0x60
	v_or_b32_e32 v144, s18, v71
	v_lshlrev_b32_e32 v144, 9, v144
	v_mov_b32_e32 v145, v33
	v_lshl_add_u64 v[146:147], v[34:35], 0, v[144:145]
	s_lshl_b32 s19, s16, 3
	s_andn2_b32 s19, s19, 31
	v_or_b32_e32 v148, s19, v62
	v_ashrrev_i32_e32 v149, 31, v148
	v_lshlrev_b64 v[150:151], 9, v[148:149]
	v_lshl_add_u64 v[150:151], v[36:37], 0, v[150:151]
	global_load_dwordx4 v[152:155], v[146:147], off
	global_load_dwordx4 v[156:159], v[150:151], off
	global_load_dwordx4 v[160:163], v[146:147], off offset:32
	global_load_dwordx4 v[164:167], v[150:151], off offset:32
	global_load_dwordx4 v[168:171], v[146:147], off offset:64
	global_load_dwordx4 v[172:175], v[150:151], off offset:64
	global_load_dwordx4 v[176:179], v[146:147], off offset:96
	global_load_dwordx4 v[180:183], v[150:151], off offset:96
	v_add_u32_e32 v184, s18, v65
	v_add_u32_e32 v184, 0x4000, v184
	v_ashrrev_i32_e32 v185, 31, v184
	v_lshlrev_b64 v[186:187], 10, v[184:185]
	v_lshl_add_u64 v[186:187], v[186:187], 0, v[148:149]
	v_lshlrev_b64 v[186:187], 1, v[186:187]
	v_lshl_add_u64 v[186:187], s[4:5], 0, v[186:187]
	s_movk_i32 s22, 0x1000
	s_mov_b32 s23, 0
	v_lshl_add_u64 v[186:187], v[186:187], 0, s[22:23]
	global_load_ushort v188, v[186:187], off offset:-4096
	global_load_ushort v189, v[186:187], off offset:-2048
	global_load_ushort v190, v[186:187], off
	global_load_ushort v191, v[186:187], off offset:2048
	s_movk_i32 s6, 0xffe0
	v_mov_b32_e32 v1, v0
	v_mov_b32_e32 v2, v0
	v_mov_b32_e32 v3, v0
	v_mov_b32_e32 v4, v0
	v_mov_b32_e32 v5, v0
	v_mov_b32_e32 v6, v0
	v_mov_b32_e32 v7, v0
	v_mov_b32_e32 v8, v0
	v_mov_b32_e32 v9, v0
	v_mov_b32_e32 v10, v0
	v_mov_b32_e32 v11, v0
	v_mov_b32_e32 v12, v0
	v_mov_b32_e32 v13, v0
	v_mov_b32_e32 v14, v0
	v_mov_b32_e32 v15, v0
	v_mov_b32_e32 v16, v0
	v_mov_b32_e32 v17, v0
	v_mov_b32_e32 v18, v0
	v_mov_b32_e32 v19, v0
	v_mov_b32_e32 v20, v0
	v_mov_b32_e32 v21, v0
	v_mov_b32_e32 v22, v0
	v_mov_b32_e32 v23, v0
	v_mov_b32_e32 v24, v0
	v_mov_b32_e32 v25, v0
	v_mov_b32_e32 v26, v0
	v_mov_b32_e32 v27, v0
	v_mov_b32_e32 v28, v0
	v_mov_b32_e32 v29, v0
	v_mov_b32_e32 v30, v0
	v_mov_b32_e32 v31, v0
.LBB0_725:
	global_load_dwordx4 v[80:83], v[44:45], off offset:-128
	global_load_dwordx4 v[84:87], v[42:43], off offset:-128
	global_load_dwordx4 v[88:91], v[44:45], off offset:-96
	global_load_dwordx4 v[92:95], v[42:43], off offset:-96
	global_load_dwordx4 v[96:99], v[44:45], off offset:-64
	global_load_dwordx4 v[100:103], v[42:43], off offset:-64
	global_load_dwordx4 v[104:107], v[44:45], off offset:-32
	global_load_dwordx4 v[108:111], v[42:43], off offset:-32
	global_load_dwordx4 v[112:115], v[44:45], off
	global_load_dwordx4 v[116:119], v[42:43], off
	global_load_dwordx4 v[120:123], v[44:45], off offset:32
	global_load_dwordx4 v[124:127], v[42:43], off offset:32
	global_load_dwordx4 v[128:131], v[44:45], off offset:64
	global_load_dwordx4 v[132:135], v[44:45], off offset:96
	global_load_dwordx4 v[136:139], v[42:43], off offset:64
	global_load_dwordx4 v[140:143], v[42:43], off offset:96
	s_addk_i32 s6, 0x80
	s_cmpk_lt_u32 s6, 0xe0
	v_lshl_add_u64 v[44:45], v[44:45], 0, s[2:3]
	v_lshl_add_u64 v[42:43], v[42:43], 0, s[2:3]
	s_waitcnt vmcnt(14)
	v_mfma_f32_32x32x16_bf16 v[0:15], v[80:83], v[84:87], v[0:15]
	s_waitcnt vmcnt(12)
	v_mfma_f32_32x32x16_bf16 v[16:31], v[88:91], v[92:95], v[16:31]
	s_waitcnt vmcnt(10)
	v_mfma_f32_32x32x16_bf16 v[0:15], v[96:99], v[100:103], v[0:15]
	s_waitcnt vmcnt(8)
	v_mfma_f32_32x32x16_bf16 v[16:31], v[104:107], v[108:111], v[16:31]
	s_waitcnt vmcnt(6)
	v_mfma_f32_32x32x16_bf16 v[0:15], v[112:115], v[116:119], v[0:15]
	s_waitcnt vmcnt(4)
	v_mfma_f32_32x32x16_bf16 v[16:31], v[120:123], v[124:127], v[16:31]
	s_waitcnt vmcnt(1)
	v_mfma_f32_32x32x16_bf16 v[0:15], v[128:131], v[136:139], v[0:15]
	s_waitcnt vmcnt(0)
	v_mfma_f32_32x32x16_bf16 v[16:31], v[132:135], v[140:143], v[16:31]
	s_cbranch_scc1 .LBB0_725
	s_lshl_b32 s7, s16, 5
	s_and_b32 s7, s7, 0x60
	v_or_b32_e32 v32, s7, v71
	s_nop 7
	v_add_f32_e32 v0, v0, v16
	v_add_f32_e32 v1, v1, v17
	v_add_f32_e32 v8, v8, v24
	v_add_f32_e32 v9, v9, v25
	v_lshlrev_b32_e32 v32, 9, v32
	v_add_f32_e32 v2, v2, v18
	v_add_f32_e32 v3, v3, v19
	v_add_f32_e32 v4, v4, v20
	v_add_f32_e32 v5, v5, v21
	v_add_f32_e32 v6, v6, v22
	v_add_f32_e32 v7, v7, v23
	v_add_f32_e32 v10, v10, v26
	v_add_f32_e32 v11, v11, v27
	v_add_f32_e32 v12, v12, v28
	v_add_f32_e32 v13, v13, v29
	v_add_f32_e32 v14, v14, v30
	v_add_f32_e32 v15, v15, v31
	s_barrier
	ds_write2st64_b32 v63, v0, v1 offset1:1
	ds_write2st64_b32 v63, v2, v3 offset0:2 offset1:3
	ds_write2st64_b32 v63, v4, v5 offset0:4 offset1:5
	ds_write2st64_b32 v63, v6, v7 offset0:6 offset1:7
	ds_write2st64_b32 v63, v8, v9 offset0:8 offset1:9
	ds_write2st64_b32 v63, v10, v11 offset0:10 offset1:11
	ds_write2st64_b32 v63, v12, v13 offset0:12 offset1:13
	ds_write2st64_b32 v63, v14, v15 offset0:14 offset1:15
	v_lshl_add_u64 v[8:9], v[34:35], 0, v[32:33]
	s_waitcnt lgkmcnt(0)
	s_barrier
	s_lshl_b32 s6, s16, 3
	s_andn2_b32 s6, s6, 31
	v_or_b32_e32 v42, s6, v62
	v_ashrrev_i32_e32 v43, 31, v42
	v_lshlrev_b64 v[4:5], 9, v[42:43]
	v_lshl_add_u64 v[24:25], v[36:37], 0, v[4:5]
	v_add_u32_e32 v32, s7, v65
	v_add_u32_e32 v60, 0x4000, v32
	v_ashrrev_i32_e32 v61, 31, v60
	ds_read2st64_b32 v[52:53], v64 offset1:1
	ds_read2st64_b32 v[54:55], v64 offset0:16 offset1:17
	ds_read2st64_b32 v[44:45], v64 offset0:18 offset1:19
	ds_read2st64_b32 v[46:47], v64 offset0:2 offset1:3
	ds_read2st64_b32 v[56:57], v64 offset0:32 offset1:33
	ds_read2st64_b32 v[58:59], v64 offset0:48 offset1:49
	ds_read2st64_b32 v[48:49], v64 offset0:50 offset1:51
	ds_read2st64_b32 v[50:51], v64 offset0:34 offset1:35
	s_waitcnt lgkmcnt(0)
	s_barrier
	v_mfma_f32_32x32x16_bf16 v[16:31], v[160:163], v[164:167], 0
	v_mfma_f32_32x32x16_bf16 v[0:15], v[152:155], v[156:159], 0
	v_mfma_f32_32x32x16_bf16 v[0:15], v[168:171], v[172:175], v[0:15]
	v_lshlrev_b64 v[72:73], 10, v[60:61]
	v_lshl_add_u64 v[72:73], v[72:73], 0, v[42:43]
	v_lshlrev_b64 v[72:73], 1, v[72:73]
	v_lshl_add_u64 v[74:75], s[4:5], 0, v[72:73]
	v_mfma_f32_32x32x16_bf16 v[16:31], v[176:179], v[180:183], v[16:31]
	s_nop 11
	v_add_f32_e32 v0, v0, v16
	v_add_f32_e32 v1, v1, v17
	v_add_f32_e32 v2, v2, v18
	v_add_f32_e32 v3, v3, v19
	v_add_f32_e32 v4, v4, v20
	v_add_f32_e32 v5, v5, v21
	v_add_f32_e32 v6, v6, v22
	v_add_f32_e32 v7, v7, v23
	v_add_f32_e32 v8, v8, v24
	v_add_f32_e32 v9, v9, v25
	v_add_f32_e32 v10, v10, v26
	v_add_f32_e32 v11, v11, v27
	v_add_f32_e32 v12, v12, v28
	v_add_f32_e32 v13, v13, v29
	v_add_f32_e32 v14, v14, v30
	v_add_f32_e32 v15, v15, v31
	ds_write2st64_b32 v63, v0, v1 offset1:1
	ds_write2st64_b32 v63, v2, v3 offset0:2 offset1:3
	ds_write2st64_b32 v63, v4, v5 offset0:4 offset1:5
	ds_write2st64_b32 v63, v6, v7 offset0:6 offset1:7
	ds_write2st64_b32 v63, v8, v9 offset0:8 offset1:9
	ds_write2st64_b32 v63, v10, v11 offset0:10 offset1:11
	ds_write2st64_b32 v63, v12, v13 offset0:12 offset1:13
	ds_write2st64_b32 v63, v14, v15 offset0:14 offset1:15
	s_waitcnt lgkmcnt(0)
	s_barrier
	ds_read2st64_b32 v[8:9], v64 offset1:1
	ds_read2st64_b32 v[10:11], v64 offset0:16 offset1:17
	v_add_f32_e32 v0, v52, v54
	v_add_f32_e32 v0, v0, v56
	v_add_f32_e32 v4, v0, v58
	v_mul_f32_e32 v4, 0xbfb8aa3b, v4
	s_waitcnt lgkmcnt(0)
	v_add_f32_e32 v8, v8, v10
	v_exp_f32_e32 v10, v4
	ds_read2st64_b32 v[0:1], v64 offset0:18 offset1:19
	ds_read2st64_b32 v[2:3], v64 offset0:2 offset1:3
	ds_read2st64_b32 v[12:13], v64 offset0:32 offset1:33
	ds_read2st64_b32 v[14:15], v64 offset0:48 offset1:49
	ds_read2st64_b32 v[4:5], v64 offset0:50 offset1:51
	ds_read2st64_b32 v[6:7], v64 offset0:34 offset1:35
	v_add_f32_e32 v10, 1.0, v10
	v_rcp_f32_e32 v10, v10
	s_waitcnt lgkmcnt(3)
	v_add_f32_e32 v8, v8, v12
	s_waitcnt lgkmcnt(2)
	v_add_f32_e32 v8, v8, v14
	v_lshlrev_b32_e32 v12, 16, v188
	v_fmac_f32_e32 v12, v10, v8
	v_mul_f32_e32 v8, v12, v12
	ds_bpermute_b32 v8, v66, v8
	v_lshl_add_u64 v[16:17], s[8:9], 0, v[72:73]
	s_waitcnt lgkmcnt(0)
	v_fmac_f32_e32 v8, v12, v12
	ds_bpermute_b32 v10, v67, v8
	v_cvt_pk_bf16_f32 v12, v12, s0
	global_store_short v[16:17], v12, off
	s_waitcnt lgkmcnt(0)
	v_add_f32_e32 v8, v8, v10
	ds_bpermute_b32 v10, v68, v8
	s_waitcnt lgkmcnt(0)
	v_add_f32_e32 v8, v8, v10
	ds_bpermute_b32 v10, v69, v8
	s_waitcnt lgkmcnt(0)
	v_add_f32_e32 v8, v8, v10
	ds_bpermute_b32 v10, v70, v8
	s_and_saveexec_b64 s[6:7], vcc
	s_cbranch_execz .LBB0_728
	s_waitcnt lgkmcnt(0)
	v_add_f32_e32 v8, v8, v10
	v_lshl_add_u64 v[16:17], v[60:61], 2, s[10:11]
	global_atomic_add_f32 v[16:17], v8, off
.LBB0_728:
	s_or_b64 exec, exec, s[6:7]
	v_add_u32_e32 v16, 0x4001, v32
	v_ashrrev_i32_e32 v17, 31, v16
	v_lshlrev_b64 v[18:19], 10, v[16:17]
	v_lshl_add_u64 v[18:19], v[18:19], 0, v[42:43]
	v_lshlrev_b64 v[18:19], 1, v[18:19]
	v_lshl_add_u64 v[20:21], s[4:5], 0, v[18:19]
	s_waitcnt lgkmcnt(0)
	v_add_f32_e32 v10, v53, v55
	v_add_f32_e32 v10, v10, v57
	v_add_f32_e32 v10, v10, v59
	v_mul_f32_e32 v10, 0xbfb8aa3b, v10
	v_exp_f32_e32 v10, v10
	v_add_f32_e32 v9, v9, v11
	v_add_f32_e32 v9, v9, v13
	v_add_f32_e32 v9, v9, v15
	v_add_f32_e32 v10, 1.0, v10
	v_rcp_f32_e32 v10, v10
	v_lshlrev_b32_e32 v11, 16, v189
	v_fmac_f32_e32 v11, v10, v9
	v_mul_f32_e32 v8, v11, v11
	ds_bpermute_b32 v8, v66, v8
	v_cvt_pk_bf16_f32 v12, v11, s0
	s_waitcnt lgkmcnt(0)
	v_fmac_f32_e32 v8, v11, v11
	ds_bpermute_b32 v9, v67, v8
	v_lshl_add_u64 v[10:11], s[8:9], 0, v[18:19]
	global_store_short v[10:11], v12, off
	s_waitcnt lgkmcnt(0)
	v_add_f32_e32 v8, v8, v9
	ds_bpermute_b32 v9, v68, v8
	s_waitcnt lgkmcnt(0)
	v_add_f32_e32 v8, v8, v9
	ds_bpermute_b32 v9, v69, v8
	s_waitcnt lgkmcnt(0)
	v_add_f32_e32 v8, v8, v9
	ds_bpermute_b32 v9, v70, v8
	s_and_saveexec_b64 s[6:7], vcc
	s_cbranch_execz .LBB0_730
	s_waitcnt lgkmcnt(0)
	v_add_f32_e32 v10, v8, v9
	v_lshl_add_u64 v[8:9], v[16:17], 2, s[10:11]
	global_atomic_add_f32 v[8:9], v10, off
.LBB0_730:
	s_or_b64 exec, exec, s[6:7]
	v_add_u32_e32 v8, 0x4002, v32
	s_waitcnt lgkmcnt(0)
	v_ashrrev_i32_e32 v9, 31, v8
	v_lshlrev_b64 v[10:11], 10, v[8:9]
	v_lshl_add_u64 v[10:11], v[10:11], 0, v[42:43]
	v_lshlrev_b64 v[10:11], 1, v[10:11]
	v_lshl_add_u64 v[12:13], s[4:5], 0, v[10:11]
	v_add_f32_e32 v13, v46, v44
	v_add_f32_e32 v13, v13, v50
	v_add_f32_e32 v13, v13, v48
	v_mul_f32_e32 v13, 0xbfb8aa3b, v13
	v_exp_f32_e32 v13, v13
	v_add_f32_e32 v0, v2, v0
	v_add_f32_e32 v0, v0, v6
	v_add_f32_e32 v0, v0, v4
	v_add_f32_e32 v2, 1.0, v13
	v_rcp_f32_e32 v2, v2
	v_lshl_add_u64 v[10:11], s[8:9], 0, v[10:11]
	v_lshlrev_b32_e32 v4, 16, v190
	v_fmac_f32_e32 v4, v2, v0
	v_mul_f32_e32 v0, v4, v4
	ds_bpermute_b32 v0, v66, v0
	s_waitcnt lgkmcnt(0)
	v_fmac_f32_e32 v0, v4, v4
	ds_bpermute_b32 v2, v67, v0
	v_cvt_pk_bf16_f32 v4, v4, s0
	global_store_short v[10:11], v4, off
	s_waitcnt lgkmcnt(0)
	v_add_f32_e32 v0, v0, v2
	ds_bpermute_b32 v2, v68, v0
	s_waitcnt lgkmcnt(0)
	v_add_f32_e32 v0, v0, v2
	ds_bpermute_b32 v2, v69, v0
	s_waitcnt lgkmcnt(0)
	v_add_f32_e32 v0, v0, v2
	ds_bpermute_b32 v2, v70, v0
	s_and_saveexec_b64 s[6:7], vcc
	s_cbranch_execz .LBB0_732
	s_waitcnt lgkmcnt(0)
	v_add_f32_e32 v0, v0, v2
	v_lshl_add_u64 v[8:9], v[8:9], 2, s[10:11]
	global_atomic_add_f32 v[8:9], v0, off
.LBB0_732:
	s_or_b64 exec, exec, s[6:7]
	v_add_u32_e32 v8, 0x4003, v32
	v_ashrrev_i32_e32 v9, 31, v8
	v_lshlrev_b64 v[10:11], 10, v[8:9]
	v_lshl_add_u64 v[10:11], v[10:11], 0, v[42:43]
	v_lshlrev_b64 v[10:11], 1, v[10:11]
	v_lshl_add_u64 v[12:13], s[4:5], 0, v[10:11]
	s_waitcnt lgkmcnt(0)
	v_add_f32_e32 v2, v47, v45
	v_add_f32_e32 v2, v2, v51
	v_add_f32_e32 v2, v2, v49
	v_mul_f32_e32 v2, 0xbfb8aa3b, v2
	v_exp_f32_e32 v2, v2
	v_add_f32_e32 v1, v3, v1
	v_add_f32_e32 v1, v1, v7
	v_add_f32_e32 v1, v1, v5
	v_add_f32_e32 v2, 1.0, v2
	v_rcp_f32_e32 v2, v2
	v_lshlrev_b32_e32 v3, 16, v191
	v_fmac_f32_e32 v3, v2, v1
	v_mul_f32_e32 v0, v3, v3
	ds_bpermute_b32 v0, v66, v0
	v_cvt_pk_bf16_f32 v4, v3, s0
	s_waitcnt lgkmcnt(0)
	v_fmac_f32_e32 v0, v3, v3
	ds_bpermute_b32 v1, v67, v0
	v_lshl_add_u64 v[2:3], s[8:9], 0, v[10:11]
	global_store_short v[2:3], v4, off
	s_waitcnt lgkmcnt(0)
	v_add_f32_e32 v0, v0, v1
	ds_bpermute_b32 v1, v68, v0
	s_waitcnt lgkmcnt(0)
	v_add_f32_e32 v0, v0, v1
	ds_bpermute_b32 v1, v69, v0
	s_waitcnt lgkmcnt(0)
	v_add_f32_e32 v0, v0, v1
	ds_bpermute_b32 v1, v70, v0
	s_and_saveexec_b64 s[6:7], vcc
	s_cbranch_execz .LBB0_723
	s_waitcnt lgkmcnt(0)
	v_add_f32_e32 v2, v0, v1
	v_lshl_add_u64 v[0:1], v[8:9], 2, s[10:11]
	global_atomic_add_f32 v[0:1], v2, off
	s_branch .LBB0_723

.LBB0_797:
	s_and_b32 s7, s1, 0xffffffe0
	v_or_b32_e32 v0, s7, v42
	v_ashrrev_i32_e32 v1, 31, v0
	s_lshl_b32 s7, s0, 11
	v_lshlrev_b64 v[0:1], 11, v[0:1]
	s_and_b32 s7, s7, 0x30000
	v_lshl_add_u64 v[36:37], v[32:33], 0, v[0:1]
	v_lshl_or_b32 v164, v46, 1, s7
	v_mov_b32_e32 v0, 0
	s_lshl_b32 s6, s28, 5
	s_and_b32 s6, s6, 0x60
	v_add_u32_e32 v204, s6, v45
	v_add_u32_e32 v204, 0x4000, v204
	v_ashrrev_i32_e32 v205, 31, v204
	v_lshl_add_u64 v[204:205], v[204:205], 2, s[24:25]
	global_load_dwordx4 v[200:203], v[204:205], off
	s_movk_i32 s6, 0xffe0
	v_lshl_add_u64 v[38:39], v[34:35], 0, v[164:165]
	v_mov_b32_e32 v1, v0
	v_mov_b32_e32 v2, v0
	v_mov_b32_e32 v3, v0
	v_mov_b32_e32 v4, v0
	v_mov_b32_e32 v5, v0
	v_mov_b32_e32 v6, v0
	v_mov_b32_e32 v7, v0
	v_mov_b32_e32 v8, v0
	v_mov_b32_e32 v9, v0
	v_mov_b32_e32 v10, v0
	v_mov_b32_e32 v11, v0
	v_mov_b32_e32 v12, v0
	v_mov_b32_e32 v13, v0
	v_mov_b32_e32 v14, v0
	v_mov_b32_e32 v15, v0
	v_mov_b32_e32 v16, v0
	v_mov_b32_e32 v17, v0
	v_mov_b32_e32 v18, v0
	v_mov_b32_e32 v19, v0
	v_mov_b32_e32 v20, v0
	v_mov_b32_e32 v21, v0
	v_mov_b32_e32 v22, v0
	v_mov_b32_e32 v23, v0
	v_mov_b32_e32 v24, v0
	v_mov_b32_e32 v25, v0
	v_mov_b32_e32 v26, v0
	v_mov_b32_e32 v27, v0
	v_mov_b32_e32 v28, v0
	v_mov_b32_e32 v29, v0
	v_mov_b32_e32 v30, v0
	v_mov_b32_e32 v31, v0
.LBB0_798:
	global_load_dwordx4 v[72:75], v[38:39], off offset:-128
	global_load_dwordx4 v[76:79], v[36:37], off offset:-128
	global_load_dwordx4 v[80:83], v[38:39], off offset:-96
	global_load_dwordx4 v[84:87], v[36:37], off offset:-96
	global_load_dwordx4 v[88:91], v[38:39], off offset:-64
	global_load_dwordx4 v[92:95], v[36:37], off offset:-64
	global_load_dwordx4 v[96:99], v[38:39], off offset:-32
	global_load_dwordx4 v[100:103], v[36:37], off offset:-32
	global_load_dwordx4 v[104:107], v[38:39], off
	global_load_dwordx4 v[108:111], v[36:37], off
	global_load_dwordx4 v[112:115], v[38:39], off offset:32
	global_load_dwordx4 v[116:119], v[36:37], off offset:32
	global_load_dwordx4 v[120:123], v[38:39], off offset:64
	global_load_dwordx4 v[124:127], v[38:39], off offset:96
	global_load_dwordx4 v[128:131], v[36:37], off offset:64
	global_load_dwordx4 v[132:135], v[36:37], off offset:96
	s_addk_i32 s6, 0x80
	s_cmpk_lt_u32 s6, 0xe0
	v_lshl_add_u64 v[38:39], v[38:39], 0, s[52:53]
	v_lshl_add_u64 v[36:37], v[36:37], 0, s[52:53]
	s_waitcnt vmcnt(14)
	v_mfma_f32_32x32x16_bf16 v[0:15], v[72:75], v[76:79], v[0:15]
	s_waitcnt vmcnt(12)
	v_mfma_f32_32x32x16_bf16 v[16:31], v[80:83], v[84:87], v[16:31]
	s_waitcnt vmcnt(10)
	v_mfma_f32_32x32x16_bf16 v[0:15], v[88:91], v[92:95], v[0:15]
	s_waitcnt vmcnt(8)
	v_mfma_f32_32x32x16_bf16 v[16:31], v[96:99], v[100:103], v[16:31]
	s_waitcnt vmcnt(6)
	v_mfma_f32_32x32x16_bf16 v[0:15], v[104:107], v[108:111], v[0:15]
	s_waitcnt vmcnt(4)
	v_mfma_f32_32x32x16_bf16 v[16:31], v[112:115], v[116:119], v[16:31]
	s_waitcnt vmcnt(1)
	v_mfma_f32_32x32x16_bf16 v[0:15], v[120:123], v[128:131], v[0:15]
	s_waitcnt vmcnt(0)
	v_mfma_f32_32x32x16_bf16 v[16:31], v[124:127], v[132:135], v[16:31]
	s_cbranch_scc1 .LBB0_798
	s_nop 10
	v_add_f32_e32 v0, v0, v16
	v_add_f32_e32 v1, v1, v17
	v_add_f32_e32 v2, v2, v18
	v_add_f32_e32 v3, v3, v19
	v_add_f32_e32 v4, v4, v20
	v_add_f32_e32 v5, v5, v21
	v_add_f32_e32 v6, v6, v22
	v_add_f32_e32 v7, v7, v23
	v_add_f32_e32 v8, v8, v24
	v_add_f32_e32 v9, v9, v25
	v_add_f32_e32 v10, v10, v26
	v_add_f32_e32 v11, v11, v27
	v_add_f32_e32 v12, v12, v28
	v_add_f32_e32 v13, v13, v29
	v_add_f32_e32 v14, v14, v30
	v_add_f32_e32 v15, v15, v31
	s_barrier
	ds_write2st64_b32 v43, v0, v1 offset1:1
	ds_write2st64_b32 v43, v2, v3 offset0:2 offset1:3
	ds_write2st64_b32 v43, v4, v5 offset0:4 offset1:5
	ds_write2st64_b32 v43, v6, v7 offset0:6 offset1:7
	ds_write2st64_b32 v43, v8, v9 offset0:8 offset1:9
	ds_write2st64_b32 v43, v10, v11 offset0:10 offset1:11
	ds_write2st64_b32 v43, v12, v13 offset0:12 offset1:13
	ds_write2st64_b32 v43, v14, v15 offset0:14 offset1:15
	s_waitcnt lgkmcnt(0)
	s_barrier
	ds_read2st64_b32 v[18:19], v44 offset1:1
	ds_read2st64_b32 v[20:21], v44 offset0:16 offset1:17
	ds_read2st64_b32 v[22:23], v44 offset0:32 offset1:33
	ds_read2st64_b32 v[24:25], v44 offset0:48 offset1:49
	s_lshl_b32 s6, s28, 5
	s_and_b32 s29, s6, 0x60
	s_waitcnt lgkmcnt(2)
	v_add_f32_e32 v0, v18, v20
	s_waitcnt lgkmcnt(1)
	v_add_f32_e32 v0, v0, v22
	s_waitcnt lgkmcnt(0)
	v_add_f32_e32 v1, v0, v24
	v_add_u32_e32 v0, s29, v45
	v_add_u32_e32 v26, 0x4000, v0
	v_ashrrev_i32_e32 v27, 31, v26
	v_lshl_add_u64 v[10:11], v[26:27], 2, s[24:25]
	ds_read2st64_b32 v[2:3], v44 offset0:2 offset1:3
	ds_read2st64_b32 v[4:5], v44 offset0:18 offset1:19
	ds_read2st64_b32 v[6:7], v44 offset0:34 offset1:35
	ds_read2st64_b32 v[8:9], v44 offset0:50 offset1:51
	s_lshl_b32 s15, s28, 3
	s_and_b32 s14, s15, 0xffffffe0
	s_cmpk_gt_i32 s14, 0x7ff
	s_cselect_b64 s[8:9], -1, 0
	s_cmpk_lt_i32 s14, 0x800
	s_cselect_b64 s[6:7], -1, 0
	s_and_b32 s10, s28, 0x1fffffe0
	s_cmpk_lg_i32 s10, 0x200
	s_cselect_b64 s[12:13], -1, 0
	s_cmpk_eq_i32 s10, 0x200
	s_cselect_b64 s[10:11], -1, 0
	s_or_b64 s[6:7], s[10:11], s[6:7]
	s_bitcmp0_b32 s28, 2
	s_cselect_b64 s[10:11], -1, 0
	s_and_b64 s[10:11], s[10:11], s[6:7]
	s_waitcnt vmcnt(0)
	v_fmamk_f32 v10, v200, 0x3a800000, v230
	v_cmp_gt_f32_e32 vcc, s90, v10
	v_mul_f32_e32 v11, 0x4b800000, v10
	s_nop 0
	v_cndmask_b32_e32 v10, v10, v11, vcc
	v_rsq_f32_e32 v10, v10
	s_nop 0
	v_mul_f32_e32 v11, 0x45800000, v10
	v_cndmask_b32_e32 v10, v10, v11, vcc
	v_mul_f32_e32 v18, v1, v10
	v_cndmask_b32_e64 v1, 0, 1, s[10:11]
	v_cmp_ne_u32_e64 s[6:7], 1, v1
	s_andn2_b64 vcc, exec, s[10:11]
	s_cbranch_vccnz .LBB0_805
	v_and_b32_e32 v10, 64, v231
	v_xor_b32_e32 v1, 8, v231
	v_add_u32_e32 v10, 64, v10
	v_cmp_lt_i32_e32 vcc, v1, v10
	s_nop 1
	v_cndmask_b32_e32 v1, v231, v1, vcc
	v_lshlrev_b32_e32 v1, 2, v1
	ds_bpermute_b32 v10, v1, v18
	v_mul_f32_e32 v1, v40, v18
	s_waitcnt lgkmcnt(0)
	v_mul_f32_e32 v10, v41, v10
	s_and_saveexec_b64 s[10:11], s[2:3]
	s_xor_b64 s[10:11], exec, s[10:11]
	v_add_f32_e32 v1, v1, v10
	v_cndmask_b32_e64 v18, v18, v1, s[4:5]
	s_andn2_saveexec_b64 s[10:11], s[10:11]
	v_sub_f32_e32 v18, v1, v10
	s_or_b64 exec, exec, s[10:11]

.LBB0_817:
	v_add_u32_e32 v18, 0x4001, v0
	v_add_f32_e32 v1, v19, v21
	v_ashrrev_i32_e32 v19, 31, v18
	v_lshl_add_u64 v[20:21], v[18:19], 2, s[24:25]
	v_add_f32_e32 v1, v1, v23
	v_add_f32_e32 v1, v1, v25
	s_nop 0
	v_fmamk_f32 v20, v201, 0x3a800000, v230
	v_cmp_gt_f32_e32 vcc, s90, v20
	v_mul_f32_e32 v21, 0x4b800000, v20
	s_nop 0
	v_cndmask_b32_e32 v20, v20, v21, vcc
	v_rsq_f32_e32 v20, v20
	s_nop 0
	v_mul_f32_e32 v21, 0x45800000, v20
	v_cndmask_b32_e32 v20, v20, v21, vcc
	v_mul_f32_e32 v1, v1, v20
	s_and_b64 vcc, exec, s[6:7]
	s_cbranch_vccnz .LBB0_823
	v_and_b32_e32 v21, 64, v231
	v_xor_b32_e32 v20, 8, v231
	v_add_u32_e32 v21, 64, v21
	v_cmp_lt_i32_e32 vcc, v20, v21
	s_nop 1
	v_cndmask_b32_e32 v20, v231, v20, vcc
	v_lshlrev_b32_e32 v20, 2, v20
	ds_bpermute_b32 v21, v20, v1
	v_mul_f32_e32 v20, v40, v1
	s_waitcnt lgkmcnt(0)
	v_mul_f32_e32 v21, v41, v21
	s_and_saveexec_b64 s[10:11], s[2:3]
	s_xor_b64 s[10:11], exec, s[10:11]
	v_add_f32_e32 v20, v20, v21
	v_cndmask_b32_e64 v1, v1, v20, s[4:5]
	s_andn2_saveexec_b64 s[10:11], s[10:11]
	v_sub_f32_e32 v1, v20, v21
	s_or_b64 exec, exec, s[10:11]

.LBB0_835:
	v_add_u32_e32 v18, 0x4002, v0
	v_ashrrev_i32_e32 v19, 31, v18
	v_lshl_add_u64 v[20:21], v[18:19], 2, s[24:25]
	v_add_f32_e32 v1, v2, v4
	v_add_f32_e32 v1, v1, v6
	v_add_f32_e32 v1, v1, v8
	s_nop 0
	v_fmamk_f32 v2, v202, 0x3a800000, v230
	v_cmp_gt_f32_e32 vcc, s90, v2
	v_mul_f32_e32 v4, 0x4b800000, v2
	s_nop 0
	v_cndmask_b32_e32 v2, v2, v4, vcc
	v_rsq_f32_e32 v2, v2
	s_nop 0
	v_mul_f32_e32 v4, 0x45800000, v2
	v_cndmask_b32_e32 v2, v2, v4, vcc
	v_mul_f32_e32 v1, v1, v2
	s_and_b64 vcc, exec, s[6:7]
	s_cbranch_vccz .LBB0_842
	s_and_b64 vcc, exec, s[10:11]
	s_mov_b64 s[60:61], -1
	s_cbranch_vccz .LBB0_847

.LBB0_839:
	v_add_u32_e32 v2, 0x4003, v0
	v_add_f32_e32 v1, v3, v5
	v_ashrrev_i32_e32 v3, 31, v2
	v_lshl_add_u64 v[4:5], v[2:3], 2, s[24:25]
	v_add_f32_e32 v1, v1, v7
	v_add_f32_e32 v1, v1, v9
	s_nop 0
	v_fmamk_f32 v4, v203, 0x3a800000, v230
	v_cmp_gt_f32_e32 vcc, s90, v4
	v_mul_f32_e32 v5, 0x4b800000, v4
	s_nop 0
	v_cndmask_b32_e32 v4, v4, v5, vcc
	v_rsq_f32_e32 v4, v4
	s_nop 0
	v_mul_f32_e32 v5, 0x45800000, v4
	v_cndmask_b32_e32 v4, v4, v5, vcc
	v_mul_f32_e32 v4, v1, v4
	s_and_b64 vcc, exec, s[6:7]
	s_cbranch_vccz .LBB0_856
	s_and_b64 vcc, exec, s[10:11]
	s_mov_b64 s[6:7], -1
	s_cbranch_vccz .LBB0_861

.LBB0_2297:
	s_and_b32 s14, s8, 0xffffffe0
	v_or_b32_e32 v0, s14, v46
	v_ashrrev_i32_e32 v1, 31, v0
	v_lshlrev_b64 v[0:1], 11, v[0:1]
	s_and_b32 s14, s10, 0x60
	v_lshl_add_u64 v[42:43], v[38:39], 0, v[0:1]
	v_add_lshl_u32 v32, v50, s14, 11
	v_mov_b32_e32 v0, 0
	v_lshl_add_u64 v[44:45], v[40:41], 0, v[32:33]
	v_readlane_b32 s18, v254, 10
	s_lshl_b32 s19, s18, 5
	s_and_b32 s19, s19, 0x60
	v_or_b32_e32 v140, s19, v50
	v_lshlrev_b32_e32 v140, 9, v140
	v_mov_b32_e32 v141, v33
	v_lshl_add_u64 v[142:143], v[34:35], 0, v[140:141]
	s_lshl_b32 s20, s18, 3
	s_andn2_b32 s20, s20, 31
	v_or_b32_e32 v144, s20, v46
	v_ashrrev_i32_e32 v145, 31, v144
	v_lshlrev_b64 v[146:147], 9, v[144:145]
	v_lshl_add_u64 v[146:147], v[36:37], 0, v[146:147]
	global_load_dwordx4 v[152:155], v[142:143], off
	global_load_dwordx4 v[156:159], v[146:147], off
	global_load_dwordx4 v[160:163], v[142:143], off offset:32
	global_load_dwordx4 v[164:167], v[146:147], off offset:32
	global_load_dwordx4 v[168:171], v[142:143], off offset:64
	global_load_dwordx4 v[172:175], v[146:147], off offset:64
	global_load_dwordx4 v[176:179], v[142:143], off offset:96
	global_load_dwordx4 v[180:183], v[146:147], off offset:96
	v_add_u32_e32 v148, s19, v49
	v_ashrrev_i32_e32 v149, 31, v148
	v_lshlrev_b64 v[150:151], 11, v[148:149]
	v_lshl_add_u64 v[150:151], s[6:7], 0, v[150:151]
	v_lshl_add_u64 v[150:151], v[144:145], 1, v[150:151]
	s_mov_b32 s22, 0x2001000
	s_mov_b32 s23, 0
	v_lshl_add_u64 v[150:151], v[150:151], 0, s[22:23]
	global_load_ushort v184, v[150:151], off offset:-4096
	global_load_ushort v185, v[150:151], off
	global_load_ushort v186, v[150:151], off offset:2048
	global_load_ushort v187, v[150:151], off offset:-2048
	s_movk_i32 s14, 0xffe0
	v_mov_b32_e32 v1, v0
	v_mov_b32_e32 v2, v0
	v_mov_b32_e32 v3, v0
	v_mov_b32_e32 v4, v0
	v_mov_b32_e32 v5, v0
	v_mov_b32_e32 v6, v0
	v_mov_b32_e32 v7, v0
	v_mov_b32_e32 v8, v0
	v_mov_b32_e32 v9, v0
	v_mov_b32_e32 v10, v0
	v_mov_b32_e32 v11, v0
	v_mov_b32_e32 v12, v0
	v_mov_b32_e32 v13, v0
	v_mov_b32_e32 v14, v0
	v_mov_b32_e32 v15, v0
	v_mov_b32_e32 v16, v0
	v_mov_b32_e32 v17, v0
	v_mov_b32_e32 v18, v0
	v_mov_b32_e32 v19, v0
	v_mov_b32_e32 v20, v0
	v_mov_b32_e32 v21, v0
	v_mov_b32_e32 v22, v0
	v_mov_b32_e32 v23, v0
	v_mov_b32_e32 v24, v0
	v_mov_b32_e32 v25, v0
	v_mov_b32_e32 v26, v0
	v_mov_b32_e32 v27, v0
	v_mov_b32_e32 v28, v0
	v_mov_b32_e32 v29, v0
	v_mov_b32_e32 v30, v0
	v_mov_b32_e32 v31, v0
.LBB0_2298:
	global_load_dwordx4 v[76:79], v[44:45], off offset:-128
	global_load_dwordx4 v[80:83], v[42:43], off offset:-128
	global_load_dwordx4 v[84:87], v[44:45], off offset:-96
	global_load_dwordx4 v[88:91], v[42:43], off offset:-96
	global_load_dwordx4 v[92:95], v[44:45], off offset:-64
	global_load_dwordx4 v[96:99], v[42:43], off offset:-64
	global_load_dwordx4 v[100:103], v[44:45], off offset:-32
	global_load_dwordx4 v[104:107], v[42:43], off offset:-32
	global_load_dwordx4 v[108:111], v[44:45], off
	global_load_dwordx4 v[112:115], v[42:43], off
	global_load_dwordx4 v[116:119], v[44:45], off offset:32
	global_load_dwordx4 v[120:123], v[42:43], off offset:32
	global_load_dwordx4 v[124:127], v[44:45], off offset:64
	global_load_dwordx4 v[128:131], v[44:45], off offset:96
	global_load_dwordx4 v[132:135], v[42:43], off offset:64
	global_load_dwordx4 v[136:139], v[42:43], off offset:96
	s_addk_i32 s14, 0x80
	s_cmpk_lt_u32 s14, 0xe0
	v_lshl_add_u64 v[44:45], v[44:45], 0, s[2:3]
	v_lshl_add_u64 v[42:43], v[42:43], 0, s[2:3]
	s_waitcnt vmcnt(14)
	v_mfma_f32_32x32x16_bf16 v[0:15], v[76:79], v[80:83], v[0:15]
	s_waitcnt vmcnt(12)
	v_mfma_f32_32x32x16_bf16 v[16:31], v[84:87], v[88:91], v[16:31]
	s_waitcnt vmcnt(10)
	v_mfma_f32_32x32x16_bf16 v[0:15], v[92:95], v[96:99], v[0:15]
	s_waitcnt vmcnt(8)
	v_mfma_f32_32x32x16_bf16 v[16:31], v[100:103], v[104:107], v[16:31]
	s_waitcnt vmcnt(6)
	v_mfma_f32_32x32x16_bf16 v[0:15], v[108:111], v[112:115], v[0:15]
	s_waitcnt vmcnt(4)
	v_mfma_f32_32x32x16_bf16 v[16:31], v[116:119], v[120:123], v[16:31]
	s_waitcnt vmcnt(1)
	v_mfma_f32_32x32x16_bf16 v[0:15], v[124:127], v[132:135], v[0:15]
	s_waitcnt vmcnt(0)
	v_mfma_f32_32x32x16_bf16 v[16:31], v[128:131], v[136:139], v[16:31]
	s_cbranch_scc1 .LBB0_2298
	v_readlane_b32 s16, v254, 10
	s_lshl_b32 s15, s16, 5
	s_and_b32 s15, s15, 0x60
	v_or_b32_e32 v32, s15, v50
	s_nop 6
	v_add_f32_e32 v0, v0, v16
	v_add_f32_e32 v1, v1, v17
	v_add_f32_e32 v8, v8, v24
	v_add_f32_e32 v9, v9, v25
	v_lshlrev_b32_e32 v32, 9, v32
	v_add_f32_e32 v2, v2, v18
	v_add_f32_e32 v3, v3, v19
	v_add_f32_e32 v4, v4, v20
	v_add_f32_e32 v5, v5, v21
	v_add_f32_e32 v6, v6, v22
	v_add_f32_e32 v7, v7, v23
	v_add_f32_e32 v10, v10, v26
	v_add_f32_e32 v11, v11, v27
	v_add_f32_e32 v12, v12, v28
	v_add_f32_e32 v13, v13, v29
	v_add_f32_e32 v14, v14, v30
	v_add_f32_e32 v15, v15, v31
	s_barrier
	ds_write2st64_b32 v47, v0, v1 offset1:1
	ds_write2st64_b32 v47, v2, v3 offset0:2 offset1:3
	ds_write2st64_b32 v47, v4, v5 offset0:4 offset1:5
	ds_write2st64_b32 v47, v6, v7 offset0:6 offset1:7
	ds_write2st64_b32 v47, v8, v9 offset0:8 offset1:9
	ds_write2st64_b32 v47, v10, v11 offset0:10 offset1:11
	ds_write2st64_b32 v47, v12, v13 offset0:12 offset1:13
	ds_write2st64_b32 v47, v14, v15 offset0:14 offset1:15
	v_lshl_add_u64 v[8:9], v[34:35], 0, v[32:33]
	s_waitcnt lgkmcnt(0)
	s_barrier
	s_lshl_b32 s14, s16, 3
	s_andn2_b32 s14, s14, 31
	v_or_b32_e32 v42, s14, v46
	v_ashrrev_i32_e32 v43, 31, v42
	v_lshlrev_b64 v[4:5], 9, v[42:43]
	v_lshl_add_u64 v[10:11], v[36:37], 0, v[4:5]
	v_add_u32_e32 v82, s15, v49
	v_ashrrev_i32_e32 v83, 31, v82
	v_lshlrev_b64 v[84:85], 11, v[82:83]
	v_lshl_add_u64 v[84:85], s[6:7], 0, v[84:85]
	v_lshl_add_u64 v[84:85], v[42:43], 1, v[84:85]
	ds_read2st64_b32 v[44:45], v48 offset1:1
	ds_read2st64_b32 v[68:69], v48 offset0:16 offset1:17
	ds_read2st64_b32 v[70:71], v48 offset0:18 offset1:19
	ds_read2st64_b32 v[72:73], v48 offset0:2 offset1:3
	ds_read2st64_b32 v[74:75], v48 offset0:32 offset1:33
	ds_read2st64_b32 v[76:77], v48 offset0:48 offset1:49
	ds_read2st64_b32 v[78:79], v48 offset0:50 offset1:51
	ds_read2st64_b32 v[80:81], v48 offset0:34 offset1:35
	s_waitcnt lgkmcnt(0)
	s_barrier
	v_readlane_b32 s14, v254, 12
	s_add_i32 s16, s16, s14
	v_readlane_b32 s15, v254, 13
	s_mov_b32 s14, s16
	v_readlane_b32 s17, v254, 11
	s_add_i32 s8, s8, s9
	s_add_i32 s10, s10, s11
	v_writelane_b32 v254, s14, 10
	s_cmpk_lt_i32 s16, 0x80
	v_mfma_f32_32x32x16_bf16 v[16:31], v[160:163], v[164:167], 0
	v_writelane_b32 v254, s15, 11
	v_mfma_f32_32x32x16_bf16 v[0:15], v[152:155], v[156:159], 0
	v_mfma_f32_32x32x16_bf16 v[0:15], v[168:171], v[172:175], v[0:15]
	v_add_co_u32_e32 v52, vcc, s12, v84
	s_nop 1
	v_addc_co_u32_e32 v53, vcc, 0, v85, vcc
	v_add_co_u32_e32 v54, vcc, s13, v84
	v_mfma_f32_32x32x16_bf16 v[16:31], v[176:179], v[180:183], v[16:31]
	v_addc_co_u32_e32 v55, vcc, 0, v85, vcc
	s_nop 10
	v_add_f32_e32 v0, v0, v16
	v_add_f32_e32 v1, v1, v17
	v_add_f32_e32 v2, v2, v18
	v_add_f32_e32 v3, v3, v19
	v_add_f32_e32 v4, v4, v20
	v_add_f32_e32 v5, v5, v21
	v_add_f32_e32 v6, v6, v22
	v_add_f32_e32 v7, v7, v23
	v_add_f32_e32 v8, v8, v24
	v_add_f32_e32 v9, v9, v25
	v_add_f32_e32 v10, v10, v26
	v_add_f32_e32 v11, v11, v27
	v_add_f32_e32 v12, v12, v28
	v_add_f32_e32 v13, v13, v29
	v_add_f32_e32 v14, v14, v30
	v_add_f32_e32 v15, v15, v31
	ds_write2st64_b32 v47, v0, v1 offset1:1
	ds_write2st64_b32 v47, v2, v3 offset0:2 offset1:3
	ds_write2st64_b32 v47, v4, v5 offset0:4 offset1:5
	ds_write2st64_b32 v47, v6, v7 offset0:6 offset1:7
	ds_write2st64_b32 v47, v8, v9 offset0:8 offset1:9
	ds_write2st64_b32 v47, v10, v11 offset0:10 offset1:11
	ds_write2st64_b32 v47, v12, v13 offset0:12 offset1:13
	ds_write2st64_b32 v47, v14, v15 offset0:14 offset1:15
	s_waitcnt lgkmcnt(0)
	s_barrier
	v_or_b32_e32 v0, 1, v82
	v_or_b32_e32 v2, 2, v82
	v_or_b32_e32 v4, 3, v82
	v_ashrrev_i32_e32 v1, 31, v0
	v_ashrrev_i32_e32 v3, 31, v2
	v_ashrrev_i32_e32 v5, 31, v4
	v_lshl_add_u64 v[6:7], v[42:43], 2, s[0:1]
	v_lshlrev_b64 v[8:9], 12, v[82:83]
	v_lshlrev_b64 v[0:1], 12, v[0:1]
	v_lshlrev_b64 v[2:3], 12, v[2:3]
	v_lshlrev_b64 v[4:5], 12, v[4:5]
	v_add_f32_e32 v10, v44, v68
	v_add_f32_e32 v11, v45, v69
	v_add_f32_e32 v12, v72, v70
	v_add_f32_e32 v13, v73, v71
	v_lshl_add_u64 v[8:9], v[6:7], 0, v[8:9]
	v_lshl_add_u64 v[0:1], v[6:7], 0, v[0:1]
	v_lshl_add_u64 v[2:3], v[6:7], 0, v[2:3]
	v_lshl_add_u64 v[4:5], v[6:7], 0, v[4:5]
	v_add_f32_e32 v6, v10, v74
	v_add_f32_e32 v7, v11, v75
	v_add_f32_e32 v10, v12, v80
	v_add_f32_e32 v11, v13, v81
	v_add_f32_e32 v6, v6, v76
	v_add_f32_e32 v7, v7, v77
	v_add_f32_e32 v10, v10, v78
	v_add_f32_e32 v11, v11, v79
	v_mul_f32_e32 v6, 0xbfb8aa3b, v6
	v_mul_f32_e32 v7, 0xbfb8aa3b, v7
	v_mul_f32_e32 v10, 0xbfb8aa3b, v10
	v_mul_f32_e32 v11, 0xbfb8aa3b, v11
	v_exp_f32_e32 v6, v6
	v_exp_f32_e32 v7, v7
	v_exp_f32_e32 v10, v10
	v_exp_f32_e32 v11, v11
	v_add_f32_e32 v6, 1.0, v6
	v_add_f32_e32 v7, 1.0, v7
	v_add_f32_e32 v10, 1.0, v10
	v_add_f32_e32 v11, 1.0, v11
	v_rcp_f32_e32 v28, v6
	v_rcp_f32_e32 v29, v7
	v_rcp_f32_e32 v30, v10
	v_rcp_f32_e32 v31, v11
	ds_read2st64_b32 v[6:7], v48 offset1:1
	ds_read2st64_b32 v[10:11], v48 offset0:16 offset1:17
	ds_read2st64_b32 v[12:13], v48 offset0:18 offset1:19
	ds_read2st64_b32 v[14:15], v48 offset0:2 offset1:3
	ds_read2st64_b32 v[16:17], v48 offset0:32 offset1:33
	ds_read2st64_b32 v[18:19], v48 offset0:48 offset1:49
	ds_read2st64_b32 v[20:21], v48 offset0:50 offset1:51
	ds_read2st64_b32 v[22:23], v48 offset0:34 offset1:35
	s_waitcnt lgkmcnt(6)
	v_add_f32_e32 v6, v6, v10
	v_add_f32_e32 v7, v7, v11
	s_waitcnt lgkmcnt(4)
	v_add_f32_e32 v10, v14, v12
	v_add_f32_e32 v11, v15, v13
	s_waitcnt lgkmcnt(3)
	v_add_f32_e32 v6, v6, v16
	v_add_f32_e32 v7, v7, v17
	s_waitcnt lgkmcnt(0)
	v_add_f32_e32 v10, v10, v22
	v_add_f32_e32 v11, v11, v23
	v_add_f32_e32 v6, v6, v18
	v_add_f32_e32 v7, v7, v19
	v_add_f32_e32 v10, v10, v20
	v_add_f32_e32 v11, v11, v21
	v_lshlrev_b32_e32 v12, 16, v184
	v_lshlrev_b32_e32 v14, 16, v185
	v_lshlrev_b32_e32 v15, 16, v186
	v_lshlrev_b32_e32 v13, 16, v187
	v_fmac_f32_e32 v12, v28, v6
	v_fmac_f32_e32 v13, v29, v7
	v_fmac_f32_e32 v14, v30, v10
	v_fmac_f32_e32 v15, v31, v11
	global_store_dword v[8:9], v12, off
	global_store_dword v[0:1], v13, off
	global_store_dword v[2:3], v14, off
	global_store_dword v[4:5], v15, off
	s_cbranch_scc1 .LBB0_2297
	s_branch .LBB0_2300
